# MLP-up GEMM: per-tile epilogue-alignment barrier pair removed (leading half starts its epilogue while the trailing half runs its last MFMA block), on the load-segment priority version
# baseline (speedup 1.0000x reference)
.LBB0_2428:
	s_add_u32 s8, s4, 0xfffc0080
	s_addc_u32 s9, s5, -1
	s_add_i32 s20, 0, 0x10000
	s_cmp_eq_u32 s70, 12
	s_cselect_b32 s53, s49, s9
	s_cselect_b32 s52, s48, s8
	v_add_u32_e32 v144, s20, v147
	s_cselect_b32 s9, s7, s69
	s_cselect_b32 s8, s47, s68
	s_add_i32 s37, 0, 0x14000
	ds_read_b128 v[140:143], v144
	ds_read_b128 v[150:153], v144 offset:1024
	ds_read_b128 v[154:157], v144 offset:2048
	ds_read_b128 v[158:161], v144 offset:3072
	v_add_u32_e32 v144, s37, v147
	ds_read_b128 v[162:165], v144
	ds_read_b128 v[166:169], v144 offset:1024
	ds_read_b128 v[170:173], v144 offset:2048
	ds_read_b128 v[174:177], v144 offset:3072
	s_add_i32 m0, s57, 0xc000
	ds_read_b128 v[178:181], v149
	ds_read_b128 v[182:185], v149 offset:1024
	ds_read_b128 v[186:189], v149 offset:2048
	ds_read_b128 v[190:193], v149 offset:3072
	ds_read_b128 v[194:197], v149 offset:4096
	ds_read_b128 v[198:201], v149 offset:5120
	ds_read_b128 v[202:205], v149 offset:6144
	ds_read_b128 v[206:209], v149 offset:7168
	global_load_lds_dwordx4 v136, s[4:5]
	s_add_i32 m0, s57, 0xe000
	s_nop 0
	global_load_lds_dwordx4 v138, s[4:5]
	s_setprio 0
	s_waitcnt vmcnt(8)
	s_waitcnt lgkmcnt(0)
	s_barrier
	s_waitcnt lgkmcnt(0)
	v_mfma_f32_16x16x32_bf16 v[126:129], v[140:143], v[178:181], v[126:129]
	v_mfma_f32_16x16x32_bf16 v[122:125], v[154:157], v[178:181], v[122:125]
	v_mfma_f32_16x16x32_bf16 v[110:113], v[140:143], v[186:189], v[110:113]
	v_mfma_f32_16x16x32_bf16 v[106:109], v[154:157], v[186:189], v[106:109]
	v_mfma_f32_16x16x32_bf16 v[94:97], v[140:143], v[194:197], v[94:97]
	v_mfma_f32_16x16x32_bf16 v[90:93], v[154:157], v[194:197], v[90:93]
	v_mfma_f32_16x16x32_bf16 v[78:81], v[140:143], v[202:205], v[78:81]
	v_mfma_f32_16x16x32_bf16 v[74:77], v[154:157], v[202:205], v[74:77]
	v_mfma_f32_16x16x32_bf16 v[126:129], v[150:153], v[182:185], v[126:129]
	v_mfma_f32_16x16x32_bf16 v[122:125], v[158:161], v[182:185], v[122:125]
	v_mfma_f32_16x16x32_bf16 v[110:113], v[150:153], v[190:193], v[110:113]
	v_mfma_f32_16x16x32_bf16 v[106:109], v[158:161], v[190:193], v[106:109]
	v_mfma_f32_16x16x32_bf16 v[94:97], v[150:153], v[198:201], v[94:97]
	v_mfma_f32_16x16x32_bf16 v[90:93], v[158:161], v[198:201], v[90:93]
	v_mfma_f32_16x16x32_bf16 v[78:81], v[150:153], v[206:209], v[78:81]
	v_mfma_f32_16x16x32_bf16 v[74:77], v[158:161], v[206:209], v[74:77]
	v_mfma_f32_16x16x32_bf16 v[118:121], v[162:165], v[178:181], v[118:121]
	v_mfma_f32_16x16x32_bf16 v[114:117], v[170:173], v[178:181], v[114:117]
	v_mfma_f32_16x16x32_bf16 v[102:105], v[162:165], v[186:189], v[102:105]
	v_mfma_f32_16x16x32_bf16 v[98:101], v[170:173], v[186:189], v[98:101]
	v_mfma_f32_16x16x32_bf16 v[86:89], v[162:165], v[194:197], v[86:89]
	v_mfma_f32_16x16x32_bf16 v[82:85], v[170:173], v[194:197], v[82:85]
	v_mfma_f32_16x16x32_bf16 v[70:73], v[162:165], v[202:205], v[70:73]
	v_mfma_f32_16x16x32_bf16 v[66:69], v[170:173], v[202:205], v[66:69]
	v_mfma_f32_16x16x32_bf16 v[118:121], v[166:169], v[182:185], v[118:121]
	v_mfma_f32_16x16x32_bf16 v[114:117], v[174:177], v[182:185], v[114:117]
	v_mfma_f32_16x16x32_bf16 v[102:105], v[166:169], v[190:193], v[102:105]
	v_mfma_f32_16x16x32_bf16 v[98:101], v[174:177], v[190:193], v[98:101]
	v_mfma_f32_16x16x32_bf16 v[86:89], v[166:169], v[198:201], v[86:89]
	v_mfma_f32_16x16x32_bf16 v[82:85], v[174:177], v[198:201], v[82:85]
	v_mfma_f32_16x16x32_bf16 v[70:73], v[166:169], v[206:209], v[70:73]
	v_mfma_f32_16x16x32_bf16 v[66:69], v[174:177], v[206:209], v[66:69]
	s_barrier
	s_setprio 1
	s_add_i32 s20, s20, s56
	v_lshl_add_u64 v[144:145], s[8:9], 0, v[0:1]
	s_mov_b32 m0, s20
	ds_read_b128 v[178:181], v149 offset:16384
	ds_read_b128 v[182:185], v149 offset:17408
	ds_read_b128 v[186:189], v149 offset:18432
	ds_read_b128 v[190:193], v149 offset:19456
	ds_read_b128 v[194:197], v149 offset:20480
	ds_read_b128 v[198:201], v149 offset:21504
	ds_read_b128 v[202:205], v149 offset:22528
	ds_read_b128 v[206:209], v149 offset:23552
	global_load_lds_dwordx4 v[144:145], off
	s_add_i32 m0, s20, 0x2000
	s_add_u32 s20, s8, 0x40000
	v_lshl_add_u64 v[210:211], s[8:9], 0, v[134:135]
	s_addc_u32 s21, s9, 0
	s_add_i32 s37, s37, s56
	global_load_lds_dwordx4 v[210:211], off
	s_mov_b32 m0, s37
	v_lshl_add_u64 v[216:217], s[52:53], 0, v[132:133]
	global_load_lds_dwordx4 v0, s[20:21]
	s_add_i32 m0, s37, 0x2000
	s_nop 0
	global_load_lds_dwordx4 v134, s[20:21]
	v_lshl_add_u64 v[214:215], s[52:53], 0, v[130:131]
	s_mov_b32 m0, s57
	s_nop 0
	global_load_lds_dwordx4 v[214:215], off
	s_mov_b32 m0, s58
	s_nop 0
	global_load_lds_dwordx4 v[216:217], off
	s_setprio 0
	s_waitcnt vmcnt(8)
	s_waitcnt lgkmcnt(0)
	s_barrier
	s_waitcnt lgkmcnt(0)
	v_mfma_f32_16x16x32_bf16 v[62:65], v[140:143], v[178:181], v[62:65]
	v_mfma_f32_16x16x32_bf16 v[58:61], v[154:157], v[178:181], v[58:61]
	v_mfma_f32_16x16x32_bf16 v[46:49], v[140:143], v[186:189], v[46:49]
	v_mfma_f32_16x16x32_bf16 v[42:45], v[154:157], v[186:189], v[42:45]
	v_mfma_f32_16x16x32_bf16 v[30:33], v[140:143], v[194:197], v[30:33]
	v_mfma_f32_16x16x32_bf16 v[26:29], v[154:157], v[194:197], v[26:29]
	v_mfma_f32_16x16x32_bf16 v[14:17], v[140:143], v[202:205], v[14:17]
	v_mfma_f32_16x16x32_bf16 v[10:13], v[154:157], v[202:205], v[10:13]
	v_mfma_f32_16x16x32_bf16 v[62:65], v[150:153], v[182:185], v[62:65]
	v_mfma_f32_16x16x32_bf16 v[58:61], v[158:161], v[182:185], v[58:61]
	v_mfma_f32_16x16x32_bf16 v[46:49], v[150:153], v[190:193], v[46:49]
	v_mfma_f32_16x16x32_bf16 v[42:45], v[158:161], v[190:193], v[42:45]
	v_mfma_f32_16x16x32_bf16 v[30:33], v[150:153], v[198:201], v[30:33]
	v_mfma_f32_16x16x32_bf16 v[26:29], v[158:161], v[198:201], v[26:29]
	v_mfma_f32_16x16x32_bf16 v[14:17], v[150:153], v[206:209], v[14:17]
	v_mfma_f32_16x16x32_bf16 v[10:13], v[158:161], v[206:209], v[10:13]
	v_mfma_f32_16x16x32_bf16 v[54:57], v[162:165], v[178:181], v[54:57]
	v_mfma_f32_16x16x32_bf16 v[50:53], v[170:173], v[178:181], v[50:53]
	v_mfma_f32_16x16x32_bf16 v[38:41], v[162:165], v[186:189], v[38:41]
	v_mfma_f32_16x16x32_bf16 v[34:37], v[170:173], v[186:189], v[34:37]
	v_mfma_f32_16x16x32_bf16 v[22:25], v[162:165], v[194:197], v[22:25]
	v_mfma_f32_16x16x32_bf16 v[18:21], v[170:173], v[194:197], v[18:21]
	v_mfma_f32_16x16x32_bf16 v[6:9], v[162:165], v[202:205], v[6:9]
	v_mfma_f32_16x16x32_bf16 v[2:5], v[170:173], v[202:205], v[2:5]
	v_mfma_f32_16x16x32_bf16 v[54:57], v[166:169], v[182:185], v[54:57]
	v_mfma_f32_16x16x32_bf16 v[50:53], v[174:177], v[182:185], v[50:53]
	v_mfma_f32_16x16x32_bf16 v[38:41], v[166:169], v[190:193], v[38:41]
	v_mfma_f32_16x16x32_bf16 v[34:37], v[174:177], v[190:193], v[34:37]
	v_mfma_f32_16x16x32_bf16 v[22:25], v[166:169], v[198:201], v[22:25]
	v_mfma_f32_16x16x32_bf16 v[18:21], v[174:177], v[198:201], v[18:21]
	v_mfma_f32_16x16x32_bf16 v[6:9], v[166:169], v[206:209], v[6:9]
	v_mfma_f32_16x16x32_bf16 v[2:5], v[174:177], v[206:209], v[2:5]
	s_barrier
	s_setprio 1
	s_add_i32 s37, 0, 0x18000
	s_add_i32 s71, 0, 0x1c000
	v_add_u32_e32 v158, s37, v147
	v_add_u32_e32 v174, s71, v147
	ds_read_b128 v[140:143], v158
	ds_read_b128 v[150:153], v158 offset:1024
	ds_read_b128 v[154:157], v158 offset:2048
	ds_read_b128 v[158:161], v158 offset:3072
	ds_read_b128 v[162:165], v174
	ds_read_b128 v[166:169], v174 offset:1024
	ds_read_b128 v[170:173], v174 offset:2048
	ds_read_b128 v[174:177], v174 offset:3072
	s_add_u32 s20, s52, 0x40000
	s_addc_u32 s21, s53, 0
	s_mov_b32 m0, s59
	ds_read_b128 v[178:181], v149 offset:32768
	ds_read_b128 v[182:185], v149 offset:33792
	ds_read_b128 v[186:189], v149 offset:34816
	ds_read_b128 v[190:193], v149 offset:35840
	ds_read_b128 v[194:197], v149 offset:36864
	ds_read_b128 v[198:201], v149 offset:37888
	ds_read_b128 v[202:205], v149 offset:38912
	ds_read_b128 v[206:209], v149 offset:39936
	global_load_lds_dwordx4 v130, s[20:21]
	v_lshl_add_u64 v[218:219], s[20:21], 0, v[132:133]
	s_mov_b32 m0, s60
	s_nop 0
	global_load_lds_dwordx4 v[218:219], off
	s_setprio 0
	s_waitcnt vmcnt(8)
	s_waitcnt lgkmcnt(0)
	s_barrier
	s_waitcnt lgkmcnt(0)
	v_mfma_f32_16x16x32_bf16 v[126:129], v[140:143], v[178:181], v[126:129]
	v_mfma_f32_16x16x32_bf16 v[122:125], v[154:157], v[178:181], v[122:125]
	v_mfma_f32_16x16x32_bf16 v[110:113], v[140:143], v[186:189], v[110:113]
	v_mfma_f32_16x16x32_bf16 v[106:109], v[154:157], v[186:189], v[106:109]
	v_mfma_f32_16x16x32_bf16 v[94:97], v[140:143], v[194:197], v[94:97]
	v_mfma_f32_16x16x32_bf16 v[90:93], v[154:157], v[194:197], v[90:93]
	v_mfma_f32_16x16x32_bf16 v[78:81], v[140:143], v[202:205], v[78:81]
	v_mfma_f32_16x16x32_bf16 v[74:77], v[154:157], v[202:205], v[74:77]
	v_mfma_f32_16x16x32_bf16 v[126:129], v[150:153], v[182:185], v[126:129]
	v_mfma_f32_16x16x32_bf16 v[122:125], v[158:161], v[182:185], v[122:125]
	v_mfma_f32_16x16x32_bf16 v[110:113], v[150:153], v[190:193], v[110:113]
	v_mfma_f32_16x16x32_bf16 v[106:109], v[158:161], v[190:193], v[106:109]
	v_mfma_f32_16x16x32_bf16 v[94:97], v[150:153], v[198:201], v[94:97]
	v_mfma_f32_16x16x32_bf16 v[90:93], v[158:161], v[198:201], v[90:93]
	v_mfma_f32_16x16x32_bf16 v[78:81], v[150:153], v[206:209], v[78:81]
	v_mfma_f32_16x16x32_bf16 v[74:77], v[158:161], v[206:209], v[74:77]
	v_mfma_f32_16x16x32_bf16 v[118:121], v[162:165], v[178:181], v[118:121]
	v_mfma_f32_16x16x32_bf16 v[114:117], v[170:173], v[178:181], v[114:117]
	v_mfma_f32_16x16x32_bf16 v[102:105], v[162:165], v[186:189], v[102:105]
	v_mfma_f32_16x16x32_bf16 v[98:101], v[170:173], v[186:189], v[98:101]
	v_mfma_f32_16x16x32_bf16 v[86:89], v[162:165], v[194:197], v[86:89]
	v_mfma_f32_16x16x32_bf16 v[82:85], v[170:173], v[194:197], v[82:85]
	v_mfma_f32_16x16x32_bf16 v[70:73], v[162:165], v[202:205], v[70:73]
	v_mfma_f32_16x16x32_bf16 v[66:69], v[170:173], v[202:205], v[66:69]
	v_mfma_f32_16x16x32_bf16 v[118:121], v[166:169], v[182:185], v[118:121]
	v_mfma_f32_16x16x32_bf16 v[114:117], v[174:177], v[182:185], v[114:117]
	v_mfma_f32_16x16x32_bf16 v[102:105], v[166:169], v[190:193], v[102:105]
	v_mfma_f32_16x16x32_bf16 v[98:101], v[174:177], v[190:193], v[98:101]
	v_mfma_f32_16x16x32_bf16 v[86:89], v[166:169], v[198:201], v[86:89]
	v_mfma_f32_16x16x32_bf16 v[82:85], v[174:177], v[198:201], v[82:85]
	v_mfma_f32_16x16x32_bf16 v[70:73], v[166:169], v[206:209], v[70:73]
	v_mfma_f32_16x16x32_bf16 v[66:69], v[174:177], v[206:209], v[66:69]
	s_barrier
	s_setprio 1
	s_add_i32 s20, s37, s56
	v_lshl_add_u64 v[144:145], v[144:145], 0, s[24:25]
	s_mov_b32 m0, s20
	ds_read_b128 v[178:181], v149 offset:49152
	ds_read_b128 v[182:185], v149 offset:50176
	ds_read_b128 v[186:189], v149 offset:51200
	ds_read_b128 v[190:193], v149 offset:52224
	ds_read_b128 v[194:197], v149 offset:53248
	ds_read_b128 v[198:201], v149 offset:54272
	ds_read_b128 v[202:205], v149 offset:55296
	ds_read_b128 v[206:209], v149 offset:56320
	global_load_lds_dwordx4 v[144:145], off
	s_add_i32 m0, s20, 0x2000
	s_add_u32 s8, s8, 0x40080
	v_lshl_add_u64 v[144:145], v[210:211], 0, s[24:25]
	s_addc_u32 s9, s9, 0
	s_add_i32 s20, s71, s56
	global_load_lds_dwordx4 v[144:145], off
	s_mov_b32 m0, s20
	s_nop 0
	global_load_lds_dwordx4 v0, s[8:9]
	s_add_i32 m0, s20, 0x2000
	s_nop 0
	global_load_lds_dwordx4 v134, s[8:9]
	v_lshl_add_u64 v[144:145], v[214:215], 0, s[24:25]
	s_mov_b32 m0, s61
	s_nop 0
	global_load_lds_dwordx4 v[144:145], off
	v_lshl_add_u64 v[144:145], v[216:217], 0, s[24:25]
	s_mov_b32 m0, s62
	s_nop 0
	global_load_lds_dwordx4 v[144:145], off
	s_setprio 0
	s_waitcnt vmcnt(8)
	s_waitcnt lgkmcnt(0)
	s_barrier
	s_waitcnt lgkmcnt(0)
	v_mfma_f32_16x16x32_bf16 v[62:65], v[140:143], v[178:181], v[62:65]
	v_mfma_f32_16x16x32_bf16 v[58:61], v[154:157], v[178:181], v[58:61]
	v_mfma_f32_16x16x32_bf16 v[46:49], v[140:143], v[186:189], v[46:49]
	v_mfma_f32_16x16x32_bf16 v[42:45], v[154:157], v[186:189], v[42:45]
	v_mfma_f32_16x16x32_bf16 v[30:33], v[140:143], v[194:197], v[30:33]
	v_mfma_f32_16x16x32_bf16 v[26:29], v[154:157], v[194:197], v[26:29]
	v_mfma_f32_16x16x32_bf16 v[14:17], v[140:143], v[202:205], v[14:17]
	v_mfma_f32_16x16x32_bf16 v[10:13], v[154:157], v[202:205], v[10:13]
	v_mfma_f32_16x16x32_bf16 v[62:65], v[150:153], v[182:185], v[62:65]
	v_mfma_f32_16x16x32_bf16 v[58:61], v[158:161], v[182:185], v[58:61]
	v_mfma_f32_16x16x32_bf16 v[46:49], v[150:153], v[190:193], v[46:49]
	v_mfma_f32_16x16x32_bf16 v[42:45], v[158:161], v[190:193], v[42:45]
	v_mfma_f32_16x16x32_bf16 v[30:33], v[150:153], v[198:201], v[30:33]
	v_mfma_f32_16x16x32_bf16 v[26:29], v[158:161], v[198:201], v[26:29]
	v_mfma_f32_16x16x32_bf16 v[14:17], v[150:153], v[206:209], v[14:17]
	v_mfma_f32_16x16x32_bf16 v[10:13], v[158:161], v[206:209], v[10:13]
	v_mfma_f32_16x16x32_bf16 v[54:57], v[162:165], v[178:181], v[54:57]
	v_mfma_f32_16x16x32_bf16 v[50:53], v[170:173], v[178:181], v[50:53]
	v_mfma_f32_16x16x32_bf16 v[38:41], v[162:165], v[186:189], v[38:41]
	v_mfma_f32_16x16x32_bf16 v[34:37], v[170:173], v[186:189], v[34:37]
	v_mfma_f32_16x16x32_bf16 v[22:25], v[162:165], v[194:197], v[22:25]
	v_mfma_f32_16x16x32_bf16 v[18:21], v[170:173], v[194:197], v[18:21]
	v_mfma_f32_16x16x32_bf16 v[6:9], v[162:165], v[202:205], v[6:9]
	v_mfma_f32_16x16x32_bf16 v[2:5], v[170:173], v[202:205], v[2:5]
	v_mfma_f32_16x16x32_bf16 v[54:57], v[166:169], v[182:185], v[54:57]
	v_mfma_f32_16x16x32_bf16 v[50:53], v[174:177], v[182:185], v[50:53]
	v_mfma_f32_16x16x32_bf16 v[38:41], v[166:169], v[190:193], v[38:41]
	v_mfma_f32_16x16x32_bf16 v[34:37], v[174:177], v[190:193], v[34:37]
	v_mfma_f32_16x16x32_bf16 v[22:25], v[166:169], v[198:201], v[22:25]
	v_mfma_f32_16x16x32_bf16 v[18:21], v[174:177], v[198:201], v[18:21]
	v_mfma_f32_16x16x32_bf16 v[6:9], v[166:169], v[206:209], v[6:9]
	v_mfma_f32_16x16x32_bf16 v[2:5], v[174:177], v[206:209], v[2:5]
	s_barrier
	s_setprio 1
	s_add_i32 s70, s70, 2
	s_add_u32 s4, s4, 0x100
	s_addc_u32 s5, s5, 0
	s_add_u32 s68, s68, 0x100
	s_addc_u32 s69, s69, 0
	s_cmp_gt_u32 s70, 13
	s_cbranch_scc0 .LBB0_2428
	s_and_b64 vcc, s[44:45], s[2:3]
	s_and_b64 vcc, exec, vcc
	s_cbranch_vccz .LBB0_2431
	s_barrier

.LBB0_2463:
	s_or_b64 exec, exec, s[4:5]
	s_and_b64 vcc, exec, s[2:3]
	s_mov_b64 s[2:3], -1
	s_cbranch_vccnz .LBB0_2418
	s_branch .LBB0_2417
